# phase 2: every workgroup's first item is static (16 scans per XCD + one 16-q-block attention group of one (b,h) per XCD), queue counter starts at 256
# baseline (speedup 1.0000x reference)
; DI void phase0(const Params& p, char* smem, const int g_wave) {
;     ...
;   if (blockIdx.x == 0 && tid == 0) { ((int*)(p.ws + WS_CTR))[0] = 0; }
; __global__ void __launch_bounds__(512) mega(Params p) {
;   extern __shared__ __attribute__((aligned(16))) char smem[];
;   cg::grid_group grid = cg::this_grid();
;   const int lo = (int)p.ph_lo, hi = (int)p.ph_hi;
;   const int g_wave = __builtin_amdgcn_readfirstlane(threadIdx.x >> 6);
;   if (lo <= 0 && hi > 0) { phase0(p, smem, g_wave); if (hi > 1) grid.sync(); }
_Z4mega6Params:
	s_load_dwordx16 s[12:27], s[0:1], 0x0
	s_load_dwordx16 s[36:51], s[0:1], 0x40
	s_load_dwordx16 s[52:67], s[0:1], 0x80
	s_load_dwordx8 s[68:75], s[0:1], 0xc0
	v_writelane_b32 v255, s2, 0
	v_and_b32_e32 v218, 0x3ff, v0
	v_mbcnt_lo_u32_b32 v1, -1, 0
	v_writelane_b32 v255, s3, 1
	s_add_u32 s2, s0, 0xe8
	s_load_dwordx2 s[84:85], s[0:1], 0xe0
	s_nop 0
	s_load_dword s0, s[0:1], 0xe8
	s_addc_u32 s3, s1, 0
	v_writelane_b32 v255, s2, 2
	s_waitcnt lgkmcnt(0)
	s_cmp_lt_i32 s74, 1
	v_readfirstlane_b32 s75, v218
	v_writelane_b32 v255, s3, 3
	v_writelane_b32 v255, s0, 4
	s_nop 1
	v_writelane_b32 v255, s1, 5
	s_cselect_b64 s[0:1], -1, 0
	s_cmp_gt_i32 s84, 0
	s_cselect_b64 s[2:3], -1, 0
	s_and_b64 s[0:1], s[0:1], s[2:3]
	s_andn2_b64 vcc, exec, s[0:1]
	s_mov_b32 s0, s84
	v_writelane_b32 v255, s0, 6
	s_nop 1
	v_writelane_b32 v255, s1, 7
	s_cbranch_vccnz .LBB0_69
	s_and_b32 s0, s75, 0xffffffc0
	v_mbcnt_hi_u32_b32 v33, -1, v1
	v_or_b32_e32 v32, s0, v33
	v_mov_b32_e32 v4, v32
	v_readlane_b32 s0, v255, 0
	v_readlane_b32 s1, v255, 1
	s_nop 0
	v_or_b32_e32 v2, s0, v4
	v_cmp_eq_u32_e32 vcc, 0, v2
	s_and_saveexec_b64 s[0:1], vcc
	s_cbranch_execz .LBB0_3
	v_mov_b32_e32 v2, 0
	v_mov_b32_e32 v250, 0x100
	global_store_dword v2, v250, s[72:73]

; #define LAUNDER_TID(t) int t = (g_wave << 6) | (int)__builtin_amdgcn_mbcnt_hi(~0u, __builtin_amdgcn_mbcnt_lo(~0u, 0u)); asm volatile("" : "+v"(t))
; DI void phase2(const Params& p, char* smem, const int g_wave) {
;     ...
;   for (;;) {
;     { LAUNDER_TID(tq); if (tq == 0) s_item = atomicAdd(ctr, 1); }
;     __syncthreads();
;     const int it = __builtin_amdgcn_readfirstlane(s_item);
;     __syncthreads();
;     if (it >= N3) break;
;     const bool is_scan = it < N0 || (it >= N1 && it < N2);
.LBB0_679:
	s_or_b64 exec, exec, s[0:1]
	s_and_b32 s0, s75, 0xffffffc0
	s_cmpk_lt_u32 s75, 0x80
	s_cselect_b32 s2, 17, 0
	s_lshr_b32 s28, s75, 7
	s_add_i32 s28, s28, 1
	s_cmpk_gt_u32 s75, 0xff
	s_cselect_b64 s[8:9], -1, 0
	s_lshl_b32 s29, s3, 3
	v_or_b32_e32 v196, s0, v2
	s_movk_i32 s6, 0x80
	v_cmp_gt_u32_e64 s[10:11], s6, v196
	s_and_saveexec_b64 s[4:5], s[10:11]
	v_lshlrev_b32_e32 v6, 2, v196
	global_load_dword v7, v6, s[44:45]
	v_add_u32_e32 v6, 0x25100, v6
	s_waitcnt vmcnt(0)
	ds_write_b32 v6, v7
	s_or_b64 exec, exec, s[4:5]
	s_sub_i32 s30, s29, 32
	s_lshl_b32 s0, s3, 4
	s_add_u32 s33, s72, 0x9641000
	s_addc_u32 s75, s73, 0
	v_writelane_b32 v255, s0, 9
	s_add_u32 s0, s72, 0x19741000
	v_writelane_b32 v255, s0, 17
	s_addc_u32 s0, s73, 0
	v_writelane_b32 v255, s0, 19
	s_add_u32 s0, s72, 0x11741000
	v_writelane_b32 v255, s0, 21
	s_addc_u32 s0, s73, 0
	v_writelane_b32 v255, s0, 23
	s_add_u32 s0, s72, 0x22841000
	v_writelane_b32 v255, s0, 10
	s_addc_u32 s0, s73, 0
	v_writelane_b32 v255, s0, 15
	s_add_u32 s0, s72, 0x1a841000
	v_writelane_b32 v255, s0, 11
	s_addc_u32 s0, s73, 0
	s_add_u32 s10, s72, 0x23941000
	s_addc_u32 s11, s73, 0
	v_writelane_b32 v255, s0, 13
	s_add_u32 s0, s70, 0x8100000
	s_addc_u32 s95, s71, 0
	s_add_u32 s16, s72, 0x239a3700
	s_addc_u32 s17, s73, 0
	s_add_u32 s18, s72, 0x239a5000
	v_writelane_b32 v255, s0, 12
	s_addc_u32 s19, s73, 0
	s_lshl_b32 s0, s3, 6
	s_add_i32 s96, s0, 16
	s_add_i32 s96, s96, 0xa100
	v_mov_b32_e32 v3, 0
	s_mov_b64 s[24:25], 0x80
	s_mov_b64 s[26:27], 0x20000
	s_mov_b32 s97, 0x3e38aa3b
	s_mov_b32 s3, 1.0
	s_mov_b32 s98, 0x800000
	s_add_i32 s99, 16, 0x1e700
	s_add_i32 s36, 16, 0x1f800
	s_movk_i32 s37, 0x90
	s_add_i32 s31, 16, 0x1ec00
	s_movk_i32 s86, 0x1900
	s_movk_i32 s87, 0x1000
	s_add_i32 s88, 16, 0x1c300
	s_movk_i32 s89, 0x7fff
	s_mov_b32 s90, 0x7060302
	s_add_i32 s91, 16, 0x1d500
	v_mov_b32_e32 v197, 0x3a27c5ac
	s_add_i32 s92, 16, 0x1a180
	s_add_i32 s93, 16, 0x18180
	s_add_i32 s94, 16, 0x100
	v_mov_b32_e32 v183, 1.0
	v_readlane_b32 s6, v255, 0
	s_nop 3
	s_lshr_b32 s4, s6, 3
	s_and_b32 s6, s6, 7
	s_lshl_b32 s6, s6, 4
	s_add_i32 s6, s6, s4
	s_cmp_lt_u32 s4, 16
	s_cselect_b32 s4, 0, 0x70
	s_add_i32 s6, s6, s4
	v_mov_b32_e32 v2, v196
	s_mov_b64 s[0:1], -1
	s_branch .Lq_static
